# v097 + the last global barrier (layer 1 k3->k4) made split-phase: XCD leaders arrive on a spare counter at k3->k4 and wait (bounded) for all XCCs at k4->k5; all 15 barriers after the prep phase are XC
# baseline (speedup 1.0000x reference)
; __global__ void __launch_bounds__(NTHREADS, 2) mega_fwd(Args args) {
;     ...
;         if (ph + 1 < args.ph_hi) {
;     ...
;             for (int e_ = 0; e_ < EXTRA_SYNCS; ++e_) { XcdBarrier b2 = bar; asm volatile("" : "+s"(b2.bar)); int tb_; asm volatile("v_mbcnt_lo_u32_b32 %0, -1, 0\n\tv_mbcnt_hi_u32_b32 %0, -1, %0\n\tv_or_b32 %0, %1, %0" : "=&v"(tb_) : "s"(wv0 << 6)); xcd_barrier(b2, tb_); }
;     ...
;             if (args.ph_lo < 0) { __threadfence(); cg::this_grid().sync(); }
;             { XcdBarrier b2 = bar; asm volatile("" : "+s"(b2.bar)); int tb_; asm volatile("v_mbcnt_lo_u32_b32 %0, -1, 0\n\tv_mbcnt_hi_u32_b32 %0, -1, %0\n\tv_or_b32 %0, %1, %0" : "=&v"(tb_) : "s"(wv0 << 6)); xcd_barrier(b2, tb_); } }
.LBB0_552:
	s_andn2_saveexec_b64 s[4:5], s[4:5]
	s_cbranch_execz .LBB0_8
	s_add_i32 s4, s70, -2
	s_cmp_lt_u32 s4, 15
	s_cbranch_scc0 .Lxb_global
	s_lshr_b32 s5, 0x7fff, s4
	s_and_b32 s5, s5, 1
	s_cbranch_scc0 .Lxb_global
	v_readfirstlane_b32 s5, v18
	s_cmp_eq_u32 s5, 0
	s_cbranch_scc0 .Lxb_global
	s_cmp_eq_u32 s4, 11
	s_cbranch_scc0 .Lxb_noarr
	v_mov_b64_e32 v[16:17], s[0:1]
	flat_atomic_add v[16:17], v221 offset:128
	s_waitcnt vmcnt(0) lgkmcnt(0)
.Lxb_noarr:
	s_cmp_eq_u32 s4, 12
	s_cbranch_scc0 .Lxb_nowait
	v_readfirstlane_b32 s5, v0
	s_mov_b32 s7, 0
.Lxb_spin:
	v_mov_b64_e32 v[16:17], s[0:1]
	flat_load_dword v18, v[16:17] offset:128 sc1
	s_waitcnt vmcnt(0) lgkmcnt(0)
	v_readfirstlane_b32 s6, v18
	s_cmp_ge_u32 s6, s5
	s_cbranch_scc1 .Lxb_nowait
	s_add_i32 s7, s7, 1
	s_cmp_lt_u32 s7, 0x10000
	s_cbranch_scc0 .Lxb_nowait
	s_sleep 1
	s_branch .Lxb_spin
.Lxb_nowait:
	s_mov_b64 s[0:1], exec
	s_branch .LBB0_7
